# v24
# speedup vs baseline: 1.0064x; 1.0064x over previous
; #define LAS __attribute__((address_space(3)))
; __device__ __forceinline__ unsigned pk2(float lo, float hi) { return pg8::cvt_pk_bf16(lo, hi); }
;     ...
;     for (int j = 0; j < 4; ++j) { const int n = (lane >> 3) + 8 * j; const LAS float* s = scr + (8 * c) * 33 + n;
;         v4u o; o.x = pk2(s[0 * 33], s[1 * 33]); o.y = pk2(s[2 * 33], s[3 * 33]); o.z = pk2(s[4 * 33], s[5 * 33]); o.w = pk2(s[6 * 33], s[7 * 33]);
;         const int drow = mode == 2 ? inproj_col(n0 + n) : drow0 + n;
;         *(v4u*)(WT + (size_t)drow * K + k0 + 8 * c) = o; }
; __device__ __forceinline__ void convert_layer(const Ctx& C, int li) {
;     ...
;     { v4u* z = (v4u*)((bf16*)(wl + WL_IN) + (size_t)NPROJ * D); const size_t n16 = (size_t)(LDP - NPROJ) * D * 2 / 16;
;       for (size_t i = (size_t)C.bid * NTHR + C.tid; i < n16; i += (size_t)C.G * NTHR) z[i] = (v4u){0u, 0u, 0u, 0u}; }
; }
; __device__ __forceinline__ void convert_p(const Ctx& C) {
;     const float* p = C.in[1]; bf16* o = (bf16*)(C.ws + WS_PBF); const size_t n8 = (size_t)2 * M * PLE / 8;
;     for (size_t i = (size_t)C.bid * NTHR + C.tid; i < n8; i += (size_t)C.G * NTHR) {
;         const f32x4 a = __builtin_nontemporal_load((const f32x4*)(p + i * 8)), b = __builtin_nontemporal_load((const f32x4*)(p + i * 8 + 4));
;         v4u w; w.x = pk2(a[0], a[1]); w.y = pk2(a[2], a[3]); w.z = pk2(b[0], b[1]); w.w = pk2(b[2], b[3]);
;         *(v4u*)(o + i * 8) = w; }
; }
.Lp0_havegs:
	s_waitcnt lgkmcnt(12)
	v_pk_mul_f32 v[52:53], v[52:53], v[12:13]
	v_pk_mul_f32 v[54:55], v[54:55], v[14:15]
	v_pk_mul_f32 v[56:57], v[56:57], v[16:17]
	v_pk_mul_f32 v[58:59], v[58:59], v[18:19]
	v_cvt_pk_bf16_f32 v84, v52, v53
	v_cvt_pk_bf16_f32 v85, v54, v55
	v_cvt_pk_bf16_f32 v86, v56, v57
	v_cvt_pk_bf16_f32 v87, v58, v59
	global_store_dwordx4 v100, v[84:87], s[50:51] sc0 sc1
	s_waitcnt lgkmcnt(8)
	v_pk_mul_f32 v[60:61], v[60:61], v[12:13]
	v_pk_mul_f32 v[62:63], v[62:63], v[14:15]
	v_pk_mul_f32 v[64:65], v[64:65], v[16:17]
	v_pk_mul_f32 v[66:67], v[66:67], v[18:19]
	v_cvt_pk_bf16_f32 v88, v60, v61
	v_cvt_pk_bf16_f32 v89, v62, v63
	v_cvt_pk_bf16_f32 v90, v64, v65
	v_cvt_pk_bf16_f32 v91, v66, v67
	global_store_dwordx4 v101, v[88:91], s[50:51] sc0 sc1
	s_waitcnt lgkmcnt(4)
	v_pk_mul_f32 v[68:69], v[68:69], v[12:13]
	v_pk_mul_f32 v[70:71], v[70:71], v[14:15]
	v_pk_mul_f32 v[72:73], v[72:73], v[16:17]
	v_pk_mul_f32 v[74:75], v[74:75], v[18:19]
	v_cvt_pk_bf16_f32 v92, v68, v69
	v_cvt_pk_bf16_f32 v93, v70, v71
	v_cvt_pk_bf16_f32 v94, v72, v73
	v_cvt_pk_bf16_f32 v95, v74, v75
	global_store_dwordx4 v102, v[92:95], s[50:51] sc0 sc1
	s_waitcnt lgkmcnt(0)
	v_pk_mul_f32 v[76:77], v[76:77], v[12:13]
	v_pk_mul_f32 v[78:79], v[78:79], v[14:15]
	v_pk_mul_f32 v[80:81], v[80:81], v[16:17]
	v_pk_mul_f32 v[82:83], v[82:83], v[18:19]
	v_cvt_pk_bf16_f32 v96, v76, v77
	v_cvt_pk_bf16_f32 v97, v78, v79
	v_cvt_pk_bf16_f32 v98, v80, v81
	v_cvt_pk_bf16_f32 v99, v82, v83
	global_store_dwordx4 v103, v[96:99], s[50:51] sc0 sc1
	s_mov_b32 s50, s70
	s_mov_b32 s51, s71
	s_mov_b32 s52, s72
	s_mov_b32 s53, s73
	s_mov_b32 s54, s74
	s_mov_b32 s55, s75
	s_mov_b32 s56, s76
	s_mov_b32 s57, s77
	s_mov_b32 s58, s59
	s_cmp_eq_u32 s63, 1
	s_cbranch_scc1 .Lp0_loop
	s_waitcnt vmcnt(0)
	v_lshl_add_u32 v11, s2, 9, v234
	s_lshl_b32 s6, s46, 9
	s_add_u32 s10, s48, 0x1620000
	s_addc_u32 s11, s49, 0
	s_add_u32 s12, s48, 0x8020000
	s_addc_u32 s13, s49, 0
	v_mov_b32_e32 v20, 0
	v_mov_b32_e32 v21, 0
	v_mov_b32_e32 v22, 0
	v_mov_b32_e32 v23, 0
	v_mov_b32_e32 v24, v11
	s_mov_b64 s[8:9], exec
.Lp0_zp:
	v_cmp_gt_u32_e32 vcc, 0xe000, v24
	s_and_b64 exec, exec, vcc
	s_cbranch_execz .Lp0_zp_done
	v_lshlrev_b32_e32 v25, 4, v24
	global_store_dwordx4 v25, v[20:23], s[10:11] sc0 sc1
	global_store_dwordx4 v25, v[20:23], s[12:13] sc0 sc1
	v_add_u32_e32 v24, s6, v24
	s_branch .Lp0_zp
.Lp0_zp_done:
	s_mov_b64 exec, s[8:9]
	v_lshlrev_b32_e32 v12, 5, v11
	v_lshlrev_b32_e32 v13, 4, v11
	s_mov_b32 s10, s66
	s_mov_b32 s11, s67
	global_load_dwordx4 v[20:23], v12, s[10:11] nt
	global_load_dwordx4 v[24:27], v12, s[10:11] offset:16 nt
	s_add_u32 s10, s10, 0x400000
	s_addc_u32 s11, s11, 0
	global_load_dwordx4 v[28:31], v12, s[10:11] nt
	global_load_dwordx4 v[32:35], v12, s[10:11] offset:16 nt
	s_add_u32 s10, s10, 0x400000
	s_addc_u32 s11, s11, 0
	global_load_dwordx4 v[36:39], v12, s[10:11] nt
	global_load_dwordx4 v[40:43], v12, s[10:11] offset:16 nt
	s_add_u32 s10, s10, 0x400000
	s_addc_u32 s11, s11, 0
	global_load_dwordx4 v[44:47], v12, s[10:11] nt
	global_load_dwordx4 v[48:51], v12, s[10:11] offset:16 nt
	s_add_u32 s10, s10, 0x400000
	s_addc_u32 s11, s11, 0
	global_load_dwordx4 v[52:55], v12, s[10:11] nt
	global_load_dwordx4 v[56:59], v12, s[10:11] offset:16 nt
	s_add_u32 s10, s10, 0x400000
	s_addc_u32 s11, s11, 0
	global_load_dwordx4 v[60:63], v12, s[10:11] nt
	global_load_dwordx4 v[64:67], v12, s[10:11] offset:16 nt
	s_add_u32 s10, s10, 0x400000
	s_addc_u32 s11, s11, 0
	global_load_dwordx4 v[68:71], v12, s[10:11] nt
	global_load_dwordx4 v[72:75], v12, s[10:11] offset:16 nt
	s_add_u32 s10, s10, 0x400000
	s_addc_u32 s11, s11, 0
	global_load_dwordx4 v[76:79], v12, s[10:11] nt
	global_load_dwordx4 v[80:83], v12, s[10:11] offset:16 nt
	s_add_u32 s12, s48, 0xd400000
	s_addc_u32 s13, s49, 0
	s_waitcnt vmcnt(14)
	v_cvt_pk_bf16_f32 v84, v20, v21
	v_cvt_pk_bf16_f32 v85, v22, v23
	v_cvt_pk_bf16_f32 v86, v24, v25
	v_cvt_pk_bf16_f32 v87, v26, v27
	global_store_dwordx4 v13, v[84:87], s[12:13] sc0 sc1
	s_add_u32 s12, s12, 0x200000
	s_addc_u32 s13, s13, 0
	s_waitcnt vmcnt(13)
	v_cvt_pk_bf16_f32 v88, v28, v29
	v_cvt_pk_bf16_f32 v89, v30, v31
	v_cvt_pk_bf16_f32 v90, v32, v33
	v_cvt_pk_bf16_f32 v91, v34, v35
	global_store_dwordx4 v13, v[88:91], s[12:13] sc0 sc1
	s_add_u32 s12, s12, 0x200000
	s_addc_u32 s13, s13, 0
	s_waitcnt vmcnt(12)
	v_cvt_pk_bf16_f32 v92, v36, v37
	v_cvt_pk_bf16_f32 v93, v38, v39
	v_cvt_pk_bf16_f32 v94, v40, v41
	v_cvt_pk_bf16_f32 v95, v42, v43
	global_store_dwordx4 v13, v[92:95], s[12:13] sc0 sc1
	s_add_u32 s12, s12, 0x200000
	s_addc_u32 s13, s13, 0
	s_waitcnt vmcnt(11)
	v_cvt_pk_bf16_f32 v96, v44, v45
	v_cvt_pk_bf16_f32 v97, v46, v47
	v_cvt_pk_bf16_f32 v98, v48, v49
	v_cvt_pk_bf16_f32 v99, v50, v51
	global_store_dwordx4 v13, v[96:99], s[12:13] sc0 sc1
	s_add_u32 s12, s12, 0x200000
	s_addc_u32 s13, s13, 0
	s_waitcnt vmcnt(10)
	v_cvt_pk_bf16_f32 v100, v52, v53
	v_cvt_pk_bf16_f32 v101, v54, v55
	v_cvt_pk_bf16_f32 v102, v56, v57
	v_cvt_pk_bf16_f32 v103, v58, v59
	global_store_dwordx4 v13, v[100:103], s[12:13] sc0 sc1
	s_add_u32 s12, s12, 0x200000
	s_addc_u32 s13, s13, 0
	s_waitcnt vmcnt(9)
	v_cvt_pk_bf16_f32 v104, v60, v61
	v_cvt_pk_bf16_f32 v105, v62, v63
	v_cvt_pk_bf16_f32 v106, v64, v65
	v_cvt_pk_bf16_f32 v107, v66, v67
	global_store_dwordx4 v13, v[104:107], s[12:13] sc0 sc1
	s_add_u32 s12, s12, 0x200000
	s_addc_u32 s13, s13, 0
	s_waitcnt vmcnt(8)
	v_cvt_pk_bf16_f32 v108, v68, v69
	v_cvt_pk_bf16_f32 v109, v70, v71
	v_cvt_pk_bf16_f32 v110, v72, v73
	v_cvt_pk_bf16_f32 v111, v74, v75
	global_store_dwordx4 v13, v[108:111], s[12:13] sc0 sc1
	s_add_u32 s12, s12, 0x200000
	s_addc_u32 s13, s13, 0
	s_waitcnt vmcnt(7)
; __device__ __forceinline__ unsigned pk2(float lo, float hi) { return pg8::cvt_pk_bf16(lo, hi); }
; __device__ __forceinline__ void xcvt_pass(const Ctx& C, const float* X, bf16* XB) {
;     const int gw = C.bid * 8 + C.wave, NGW = C.G * 8; float* SS = (float*)(C.ws + WS_SS);
;     for (int m = gw; m < M; m += NGW) {
;         const f32x4* xr = (const f32x4*)(X + (size_t)m * D) + C.lane; v2u* o = (v2u*)(XB + (size_t)m * D) + C.lane; float s = 0.f;
; #pragma unroll
;         for (int j = 0; j < 8; ++j) { const f32x4 v = __builtin_nontemporal_load(xr + 64 * j); const v2u w = (v2u){pk2(v[0], v[1]), pk2(v[2], v[3])}; o[64 * j] = w;
;             const float x0 = __uint_as_float(w.x << 16), x1 = __uint_as_float(w.x & 0xffff0000u), x2 = __uint_as_float(w.y << 16), x3 = __uint_as_float(w.y & 0xffff0000u);
;             s += (x0 * x0 + x1 * x1) + (x2 * x2 + x3 * x3); }
;         s = wave_sum(s);
;         if (C.lane < 32) SS[(size_t)m * 32 + C.lane] = C.lane == 0 ? s : 0.f;
;     }
	v_cvt_pk_bf16_f32 v112, v76, v77
	v_cvt_pk_bf16_f32 v113, v78, v79
	v_cvt_pk_bf16_f32 v114, v80, v81
	v_cvt_pk_bf16_f32 v115, v82, v83
	global_store_dwordx4 v13, v[112:115], s[12:13] sc0 sc1
	s_mov_b32 s58, s2
	s_lshl_b32 s58, s58, 3
	v_readfirstlane_b32 s6, v234
	s_lshr_b32 s6, s6, 6
	s_add_u32 s58, s58, s6
	v_lshlrev_b32_e32 v14, 4, v1
	v_lshlrev_b32_e32 v15, 3, v1
	v_lshlrev_b32_e32 v16, 2, v1
	v_xor_b32_e32 v120, 4, v16
	v_xor_b32_e32 v121, 8, v16
	v_xor_b32_e32 v122, 16, v16
	v_xor_b32_e32 v123, 32, v16
	v_xor_b32_e32 v124, 64, v16
	v_xor_b32_e32 v125, 128, v16
	s_lshl_b32 s6, s58, 13
	s_lshr_b32 s7, s58, 19
	s_add_u32 s10, s64, s6
	s_addc_u32 s11, s65, s7
	s_add_u32 s10, s10, 0x1000
	s_addc_u32 s11, s11, 0
	global_load_dwordx4 v[20:23], v14, s[10:11] offset:-4096 nt
	global_load_dwordx4 v[24:27], v14, s[10:11] offset:-3072 nt
	global_load_dwordx4 v[28:31], v14, s[10:11] offset:-2048 nt
	global_load_dwordx4 v[32:35], v14, s[10:11] offset:-1024 nt
	global_load_dwordx4 v[36:39], v14, s[10:11] offset:0 nt
	global_load_dwordx4 v[40:43], v14, s[10:11] offset:1024 nt
	global_load_dwordx4 v[44:47], v14, s[10:11] offset:2048 nt
	global_load_dwordx4 v[48:51], v14, s[10:11] offset:3072 nt
	s_lshl_b32 s6, s58, 12
	s_add_u32 s12, s48, s6
	s_addc_u32 s13, s49, 0
	s_add_u32 s12, s12, 0x26100800
	s_addc_u32 s13, s13, 0
	s_lshl_b32 s6, s58, 7
	s_add_u32 s14, s48, s6
	s_addc_u32 s15, s49, 0
	s_add_u32 s14, s14, 0x25e00000
	s_addc_u32 s15, s15, 0
	s_add_u32 s58, s58, s44
	s_lshl_b32 s6, s58, 13
	s_lshr_b32 s7, s58, 19
	s_add_u32 s10, s64, s6
	s_addc_u32 s11, s65, s7
	s_add_u32 s10, s10, 0x1000
	s_addc_u32 s11, s11, 0
	global_load_dwordx4 v[52:55], v14, s[10:11] offset:-4096 nt
	global_load_dwordx4 v[56:59], v14, s[10:11] offset:-3072 nt
	global_load_dwordx4 v[60:63], v14, s[10:11] offset:-2048 nt
	global_load_dwordx4 v[64:67], v14, s[10:11] offset:-1024 nt
	global_load_dwordx4 v[68:71], v14, s[10:11] offset:0 nt
	global_load_dwordx4 v[72:75], v14, s[10:11] offset:1024 nt
	global_load_dwordx4 v[76:79], v14, s[10:11] offset:2048 nt
	global_load_dwordx4 v[80:83], v14, s[10:11] offset:3072 nt
	s_waitcnt vmcnt(8)
	v_cvt_pk_bf16_f32 v84, v20, v21
	v_cvt_pk_bf16_f32 v85, v22, v23
	global_store_dwordx2 v15, v[84:85], s[12:13] offset:-2048 sc0 sc1
	v_lshlrev_b32_e32 v20, 16, v84
	v_and_b32_e32 v21, 0xffff0000, v84
	v_lshlrev_b32_e32 v22, 16, v85
	v_and_b32_e32 v23, 0xffff0000, v85
	v_mul_f32_e32 v21, v21, v21
	v_mul_f32_e32 v23, v23, v23
	v_fmac_f32_e32 v21, v20, v20
	v_fmac_f32_e32 v23, v22, v22
	v_add_f32_e32 v17, v21, v23
	v_cvt_pk_bf16_f32 v86, v24, v25
	v_cvt_pk_bf16_f32 v87, v26, v27
	global_store_dwordx2 v15, v[86:87], s[12:13] offset:-1536 sc0 sc1
	v_lshlrev_b32_e32 v24, 16, v86
	v_and_b32_e32 v25, 0xffff0000, v86
	v_lshlrev_b32_e32 v26, 16, v87
	v_and_b32_e32 v27, 0xffff0000, v87
	v_mul_f32_e32 v25, v25, v25
	v_mul_f32_e32 v27, v27, v27
	v_fmac_f32_e32 v25, v24, v24
	v_fmac_f32_e32 v27, v26, v26
	v_add_f32_e32 v25, v25, v27
	v_add_f32_e32 v17, v17, v25
	v_cvt_pk_bf16_f32 v88, v28, v29
	v_cvt_pk_bf16_f32 v89, v30, v31
	global_store_dwordx2 v15, v[88:89], s[12:13] offset:-1024 sc0 sc1
	v_lshlrev_b32_e32 v28, 16, v88
	v_and_b32_e32 v29, 0xffff0000, v88
	v_lshlrev_b32_e32 v30, 16, v89
	v_and_b32_e32 v31, 0xffff0000, v89
	v_mul_f32_e32 v29, v29, v29
	v_mul_f32_e32 v31, v31, v31
	v_fmac_f32_e32 v29, v28, v28
	v_fmac_f32_e32 v31, v30, v30
	v_add_f32_e32 v29, v29, v31
	v_add_f32_e32 v17, v17, v29
	v_cvt_pk_bf16_f32 v90, v32, v33
	v_cvt_pk_bf16_f32 v91, v34, v35
	global_store_dwordx2 v15, v[90:91], s[12:13] offset:-512 sc0 sc1
	v_lshlrev_b32_e32 v32, 16, v90
	v_and_b32_e32 v33, 0xffff0000, v90
	v_lshlrev_b32_e32 v34, 16, v91
	v_and_b32_e32 v35, 0xffff0000, v91
	v_mul_f32_e32 v33, v33, v33
	v_mul_f32_e32 v35, v35, v35
	v_fmac_f32_e32 v33, v32, v32
	v_fmac_f32_e32 v35, v34, v34
	v_add_f32_e32 v33, v33, v35
	v_add_f32_e32 v17, v17, v33
	v_cvt_pk_bf16_f32 v92, v36, v37
	v_cvt_pk_bf16_f32 v93, v38, v39
	global_store_dwordx2 v15, v[92:93], s[12:13] offset:0 sc0 sc1
	v_lshlrev_b32_e32 v36, 16, v92
	v_and_b32_e32 v37, 0xffff0000, v92
	v_lshlrev_b32_e32 v38, 16, v93
	v_and_b32_e32 v39, 0xffff0000, v93
	v_mul_f32_e32 v37, v37, v37
	v_mul_f32_e32 v39, v39, v39
	v_fmac_f32_e32 v37, v36, v36
	v_fmac_f32_e32 v39, v38, v38
	v_add_f32_e32 v37, v37, v39
	v_add_f32_e32 v17, v17, v37
	v_cvt_pk_bf16_f32 v94, v40, v41
	v_cvt_pk_bf16_f32 v95, v42, v43
	global_store_dwordx2 v15, v[94:95], s[12:13] offset:512 sc0 sc1
	v_lshlrev_b32_e32 v40, 16, v94
	v_and_b32_e32 v41, 0xffff0000, v94
	v_lshlrev_b32_e32 v42, 16, v95
	v_and_b32_e32 v43, 0xffff0000, v95
	v_mul_f32_e32 v41, v41, v41
	v_mul_f32_e32 v43, v43, v43
	v_fmac_f32_e32 v41, v40, v40
	v_fmac_f32_e32 v43, v42, v42
	v_add_f32_e32 v41, v41, v43
	v_add_f32_e32 v17, v17, v41
	v_cvt_pk_bf16_f32 v96, v44, v45
	v_cvt_pk_bf16_f32 v97, v46, v47
	global_store_dwordx2 v15, v[96:97], s[12:13] offset:1024 sc0 sc1
	v_lshlrev_b32_e32 v44, 16, v96
	v_and_b32_e32 v45, 0xffff0000, v96
	v_lshlrev_b32_e32 v46, 16, v97
	v_and_b32_e32 v47, 0xffff0000, v97
	v_mul_f32_e32 v45, v45, v45
	v_mul_f32_e32 v47, v47, v47
	v_fmac_f32_e32 v45, v44, v44
	v_fmac_f32_e32 v47, v46, v46
	v_add_f32_e32 v45, v45, v47
	v_add_f32_e32 v17, v17, v45
	v_cvt_pk_bf16_f32 v98, v48, v49
	v_cvt_pk_bf16_f32 v99, v50, v51
	global_store_dwordx2 v15, v[98:99], s[12:13] offset:1536 sc0 sc1
	v_lshlrev_b32_e32 v48, 16, v98
	v_and_b32_e32 v49, 0xffff0000, v98
	v_lshlrev_b32_e32 v50, 16, v99
	v_and_b32_e32 v51, 0xffff0000, v99
	v_mul_f32_e32 v49, v49, v49
	v_mul_f32_e32 v51, v51, v51
	v_fmac_f32_e32 v49, v48, v48
	v_fmac_f32_e32 v51, v50, v50
	v_add_f32_e32 v49, v49, v51
	v_add_f32_e32 v17, v17, v49
	ds_bpermute_b32 v18, v120, v17
	s_waitcnt lgkmcnt(0)
; __device__ __forceinline__ unsigned pk2(float lo, float hi) { return pg8::cvt_pk_bf16(lo, hi); }
; __device__ __forceinline__ void xcvt_pass(const Ctx& C, const float* X, bf16* XB) {
;     ...
;     for (int m = gw; m < M; m += NGW) {
;         const f32x4* xr = (const f32x4*)(X + (size_t)m * D) + C.lane; v2u* o = (v2u*)(XB + (size_t)m * D) + C.lane; float s = 0.f;
; #pragma unroll
;         for (int j = 0; j < 8; ++j) { const f32x4 v = __builtin_nontemporal_load(xr + 64 * j); const v2u w = (v2u){pk2(v[0], v[1]), pk2(v[2], v[3])}; o[64 * j] = w;
;             const float x0 = __uint_as_float(w.x << 16), x1 = __uint_as_float(w.x & 0xffff0000u), x2 = __uint_as_float(w.y << 16), x3 = __uint_as_float(w.y & 0xffff0000u);
;             s += (x0 * x0 + x1 * x1) + (x2 * x2 + x3 * x3); }
;         s = wave_sum(s);
;         if (C.lane < 32) SS[(size_t)m * 32 + C.lane] = C.lane == 0 ? s : 0.f;
;     }
	v_add_f32_e32 v17, v17, v18
	ds_bpermute_b32 v18, v121, v17
	s_waitcnt lgkmcnt(0)
	v_add_f32_e32 v17, v17, v18
	ds_bpermute_b32 v18, v122, v17
	s_waitcnt lgkmcnt(0)
	v_add_f32_e32 v17, v17, v18
	ds_bpermute_b32 v18, v123, v17
	s_waitcnt lgkmcnt(0)
	v_add_f32_e32 v17, v17, v18
	ds_bpermute_b32 v18, v124, v17
	s_waitcnt lgkmcnt(0)
	v_add_f32_e32 v17, v17, v18
	ds_bpermute_b32 v18, v125, v17
	s_waitcnt lgkmcnt(0)
	v_add_f32_e32 v17, v17, v18
	v_cmp_eq_u32_e32 vcc, 0, v1
	s_nop 1
	v_cndmask_b32_e32 v19, 0, v17, vcc
	s_mov_b64 s[8:9], exec
	s_mov_b32 exec_lo, -1
	s_mov_b32 exec_hi, 0
	global_store_dword v16, v19, s[14:15]
	s_mov_b64 exec, s[8:9]
	s_lshl_b32 s6, s58, 12
	s_add_u32 s12, s48, s6
	s_addc_u32 s13, s49, 0
	s_add_u32 s12, s12, 0x26100800
	s_addc_u32 s13, s13, 0
	s_lshl_b32 s6, s58, 7
	s_add_u32 s14, s48, s6
	s_addc_u32 s15, s49, 0
	s_add_u32 s14, s14, 0x25e00000
	s_addc_u32 s15, s15, 0
	s_add_u32 s58, s58, s44
	s_lshl_b32 s6, s58, 13
	s_lshr_b32 s7, s58, 19
	s_add_u32 s10, s64, s6
	s_addc_u32 s11, s65, s7
	s_add_u32 s10, s10, 0x1000
	s_addc_u32 s11, s11, 0
	global_load_dwordx4 v[20:23], v14, s[10:11] offset:-4096 nt
	global_load_dwordx4 v[24:27], v14, s[10:11] offset:-3072 nt
	global_load_dwordx4 v[28:31], v14, s[10:11] offset:-2048 nt
	global_load_dwordx4 v[32:35], v14, s[10:11] offset:-1024 nt
	global_load_dwordx4 v[36:39], v14, s[10:11] offset:0 nt
	global_load_dwordx4 v[40:43], v14, s[10:11] offset:1024 nt
	global_load_dwordx4 v[44:47], v14, s[10:11] offset:2048 nt
	global_load_dwordx4 v[48:51], v14, s[10:11] offset:3072 nt
	s_waitcnt vmcnt(17)
	v_cvt_pk_bf16_f32 v100, v52, v53
	v_cvt_pk_bf16_f32 v101, v54, v55
	global_store_dwordx2 v15, v[100:101], s[12:13] offset:-2048 sc0 sc1
	v_lshlrev_b32_e32 v52, 16, v100
	v_and_b32_e32 v53, 0xffff0000, v100
	v_lshlrev_b32_e32 v54, 16, v101
	v_and_b32_e32 v55, 0xffff0000, v101
	v_mul_f32_e32 v53, v53, v53
	v_mul_f32_e32 v55, v55, v55
	v_fmac_f32_e32 v53, v52, v52
	v_fmac_f32_e32 v55, v54, v54
	v_add_f32_e32 v17, v53, v55
	v_cvt_pk_bf16_f32 v102, v56, v57
	v_cvt_pk_bf16_f32 v103, v58, v59
	global_store_dwordx2 v15, v[102:103], s[12:13] offset:-1536 sc0 sc1
	v_lshlrev_b32_e32 v56, 16, v102
	v_and_b32_e32 v57, 0xffff0000, v102
	v_lshlrev_b32_e32 v58, 16, v103
	v_and_b32_e32 v59, 0xffff0000, v103
	v_mul_f32_e32 v57, v57, v57
	v_mul_f32_e32 v59, v59, v59
	v_fmac_f32_e32 v57, v56, v56
	v_fmac_f32_e32 v59, v58, v58
	v_add_f32_e32 v57, v57, v59
	v_add_f32_e32 v17, v17, v57
	v_cvt_pk_bf16_f32 v104, v60, v61
	v_cvt_pk_bf16_f32 v105, v62, v63
	global_store_dwordx2 v15, v[104:105], s[12:13] offset:-1024 sc0 sc1
	v_lshlrev_b32_e32 v60, 16, v104
	v_and_b32_e32 v61, 0xffff0000, v104
	v_lshlrev_b32_e32 v62, 16, v105
	v_and_b32_e32 v63, 0xffff0000, v105
	v_mul_f32_e32 v61, v61, v61
	v_mul_f32_e32 v63, v63, v63
	v_fmac_f32_e32 v61, v60, v60
	v_fmac_f32_e32 v63, v62, v62
	v_add_f32_e32 v61, v61, v63
	v_add_f32_e32 v17, v17, v61
	v_cvt_pk_bf16_f32 v106, v64, v65
	v_cvt_pk_bf16_f32 v107, v66, v67
	global_store_dwordx2 v15, v[106:107], s[12:13] offset:-512 sc0 sc1
	v_lshlrev_b32_e32 v64, 16, v106
	v_and_b32_e32 v65, 0xffff0000, v106
	v_lshlrev_b32_e32 v66, 16, v107
	v_and_b32_e32 v67, 0xffff0000, v107
	v_mul_f32_e32 v65, v65, v65
	v_mul_f32_e32 v67, v67, v67
	v_fmac_f32_e32 v65, v64, v64
	v_fmac_f32_e32 v67, v66, v66
	v_add_f32_e32 v65, v65, v67
	v_add_f32_e32 v17, v17, v65
	v_cvt_pk_bf16_f32 v108, v68, v69
	v_cvt_pk_bf16_f32 v109, v70, v71
	global_store_dwordx2 v15, v[108:109], s[12:13] offset:0 sc0 sc1
	v_lshlrev_b32_e32 v68, 16, v108
	v_and_b32_e32 v69, 0xffff0000, v108
	v_lshlrev_b32_e32 v70, 16, v109
	v_and_b32_e32 v71, 0xffff0000, v109
	v_mul_f32_e32 v69, v69, v69
	v_mul_f32_e32 v71, v71, v71
	v_fmac_f32_e32 v69, v68, v68
	v_fmac_f32_e32 v71, v70, v70
	v_add_f32_e32 v69, v69, v71
	v_add_f32_e32 v17, v17, v69
	v_cvt_pk_bf16_f32 v110, v72, v73
	v_cvt_pk_bf16_f32 v111, v74, v75
	global_store_dwordx2 v15, v[110:111], s[12:13] offset:512 sc0 sc1
	v_lshlrev_b32_e32 v72, 16, v110
	v_and_b32_e32 v73, 0xffff0000, v110
	v_lshlrev_b32_e32 v74, 16, v111
	v_and_b32_e32 v75, 0xffff0000, v111
	v_mul_f32_e32 v73, v73, v73
	v_mul_f32_e32 v75, v75, v75
	v_fmac_f32_e32 v73, v72, v72
	v_fmac_f32_e32 v75, v74, v74
	v_add_f32_e32 v73, v73, v75
	v_add_f32_e32 v17, v17, v73
	v_cvt_pk_bf16_f32 v112, v76, v77
	v_cvt_pk_bf16_f32 v113, v78, v79
	global_store_dwordx2 v15, v[112:113], s[12:13] offset:1024 sc0 sc1
	v_lshlrev_b32_e32 v76, 16, v112
	v_and_b32_e32 v77, 0xffff0000, v112
	v_lshlrev_b32_e32 v78, 16, v113
	v_and_b32_e32 v79, 0xffff0000, v113
	v_mul_f32_e32 v77, v77, v77
	v_mul_f32_e32 v79, v79, v79
	v_fmac_f32_e32 v77, v76, v76
	v_fmac_f32_e32 v79, v78, v78
	v_add_f32_e32 v77, v77, v79
	v_add_f32_e32 v17, v17, v77
	v_cvt_pk_bf16_f32 v114, v80, v81
	v_cvt_pk_bf16_f32 v115, v82, v83
	global_store_dwordx2 v15, v[114:115], s[12:13] offset:1536 sc0 sc1
	v_lshlrev_b32_e32 v80, 16, v114
	v_and_b32_e32 v81, 0xffff0000, v114
	v_lshlrev_b32_e32 v82, 16, v115
	v_and_b32_e32 v83, 0xffff0000, v115
	v_mul_f32_e32 v81, v81, v81
	v_mul_f32_e32 v83, v83, v83
	v_fmac_f32_e32 v81, v80, v80
	v_fmac_f32_e32 v83, v82, v82
	v_add_f32_e32 v81, v81, v83
	v_add_f32_e32 v17, v17, v81
	ds_bpermute_b32 v18, v120, v17
	s_waitcnt lgkmcnt(0)
	v_add_f32_e32 v17, v17, v18
	ds_bpermute_b32 v18, v121, v17
	s_waitcnt lgkmcnt(0)
	v_add_f32_e32 v17, v17, v18
	ds_bpermute_b32 v18, v122, v17
	s_waitcnt lgkmcnt(0)
	v_add_f32_e32 v17, v17, v18
	ds_bpermute_b32 v18, v123, v17
	s_waitcnt lgkmcnt(0)
	v_add_f32_e32 v17, v17, v18
	ds_bpermute_b32 v18, v124, v17
	s_waitcnt lgkmcnt(0)
	v_add_f32_e32 v17, v17, v18
	ds_bpermute_b32 v18, v125, v17
	s_waitcnt lgkmcnt(0)
; __device__ __forceinline__ unsigned pk2(float lo, float hi) { return pg8::cvt_pk_bf16(lo, hi); }
; __device__ __forceinline__ void xcvt_pass(const Ctx& C, const float* X, bf16* XB) {
;     ...
;     for (int m = gw; m < M; m += NGW) {
;         const f32x4* xr = (const f32x4*)(X + (size_t)m * D) + C.lane; v2u* o = (v2u*)(XB + (size_t)m * D) + C.lane; float s = 0.f;
; #pragma unroll
;         for (int j = 0; j < 8; ++j) { const f32x4 v = __builtin_nontemporal_load(xr + 64 * j); const v2u w = (v2u){pk2(v[0], v[1]), pk2(v[2], v[3])}; o[64 * j] = w;
;             const float x0 = __uint_as_float(w.x << 16), x1 = __uint_as_float(w.x & 0xffff0000u), x2 = __uint_as_float(w.y << 16), x3 = __uint_as_float(w.y & 0xffff0000u);
;             s += (x0 * x0 + x1 * x1) + (x2 * x2 + x3 * x3); }
;         s = wave_sum(s);
;         if (C.lane < 32) SS[(size_t)m * 32 + C.lane] = C.lane == 0 ? s : 0.f;
;     }
	v_add_f32_e32 v17, v17, v18
	v_cmp_eq_u32_e32 vcc, 0, v1
	s_nop 1
	v_cndmask_b32_e32 v19, 0, v17, vcc
	s_mov_b64 s[8:9], exec
	s_mov_b32 exec_lo, -1
	s_mov_b32 exec_hi, 0
	global_store_dword v16, v19, s[14:15]
	s_mov_b64 exec, s[8:9]
	s_lshl_b32 s6, s58, 12
	s_add_u32 s12, s48, s6
	s_addc_u32 s13, s49, 0
	s_add_u32 s12, s12, 0x26100800
	s_addc_u32 s13, s13, 0
	s_lshl_b32 s6, s58, 7
	s_add_u32 s14, s48, s6
	s_addc_u32 s15, s49, 0
	s_add_u32 s14, s14, 0x25e00000
	s_addc_u32 s15, s15, 0
	s_add_u32 s58, s58, s44
	s_lshl_b32 s6, s58, 13
	s_lshr_b32 s7, s58, 19
	s_add_u32 s10, s64, s6
	s_addc_u32 s11, s65, s7
	s_add_u32 s10, s10, 0x1000
	s_addc_u32 s11, s11, 0
	global_load_dwordx4 v[52:55], v14, s[10:11] offset:-4096 nt
	global_load_dwordx4 v[56:59], v14, s[10:11] offset:-3072 nt
	global_load_dwordx4 v[60:63], v14, s[10:11] offset:-2048 nt
	global_load_dwordx4 v[64:67], v14, s[10:11] offset:-1024 nt
	global_load_dwordx4 v[68:71], v14, s[10:11] offset:0 nt
	global_load_dwordx4 v[72:75], v14, s[10:11] offset:1024 nt
	global_load_dwordx4 v[76:79], v14, s[10:11] offset:2048 nt
	global_load_dwordx4 v[80:83], v14, s[10:11] offset:3072 nt
	s_waitcnt vmcnt(17)
	v_cvt_pk_bf16_f32 v84, v20, v21
	v_cvt_pk_bf16_f32 v85, v22, v23
	global_store_dwordx2 v15, v[84:85], s[12:13] offset:-2048 sc0 sc1
	v_lshlrev_b32_e32 v20, 16, v84
	v_and_b32_e32 v21, 0xffff0000, v84
	v_lshlrev_b32_e32 v22, 16, v85
	v_and_b32_e32 v23, 0xffff0000, v85
	v_mul_f32_e32 v21, v21, v21
	v_mul_f32_e32 v23, v23, v23
	v_fmac_f32_e32 v21, v20, v20
	v_fmac_f32_e32 v23, v22, v22
	v_add_f32_e32 v17, v21, v23
	v_cvt_pk_bf16_f32 v86, v24, v25
	v_cvt_pk_bf16_f32 v87, v26, v27
	global_store_dwordx2 v15, v[86:87], s[12:13] offset:-1536 sc0 sc1
	v_lshlrev_b32_e32 v24, 16, v86
	v_and_b32_e32 v25, 0xffff0000, v86
	v_lshlrev_b32_e32 v26, 16, v87
	v_and_b32_e32 v27, 0xffff0000, v87
	v_mul_f32_e32 v25, v25, v25
	v_mul_f32_e32 v27, v27, v27
	v_fmac_f32_e32 v25, v24, v24
	v_fmac_f32_e32 v27, v26, v26
	v_add_f32_e32 v25, v25, v27
	v_add_f32_e32 v17, v17, v25
	v_cvt_pk_bf16_f32 v88, v28, v29
	v_cvt_pk_bf16_f32 v89, v30, v31
	global_store_dwordx2 v15, v[88:89], s[12:13] offset:-1024 sc0 sc1
	v_lshlrev_b32_e32 v28, 16, v88
	v_and_b32_e32 v29, 0xffff0000, v88
	v_lshlrev_b32_e32 v30, 16, v89
	v_and_b32_e32 v31, 0xffff0000, v89
	v_mul_f32_e32 v29, v29, v29
	v_mul_f32_e32 v31, v31, v31
	v_fmac_f32_e32 v29, v28, v28
	v_fmac_f32_e32 v31, v30, v30
	v_add_f32_e32 v29, v29, v31
	v_add_f32_e32 v17, v17, v29
	v_cvt_pk_bf16_f32 v90, v32, v33
	v_cvt_pk_bf16_f32 v91, v34, v35
	global_store_dwordx2 v15, v[90:91], s[12:13] offset:-512 sc0 sc1
	v_lshlrev_b32_e32 v32, 16, v90
	v_and_b32_e32 v33, 0xffff0000, v90
	v_lshlrev_b32_e32 v34, 16, v91
	v_and_b32_e32 v35, 0xffff0000, v91
	v_mul_f32_e32 v33, v33, v33
	v_mul_f32_e32 v35, v35, v35
	v_fmac_f32_e32 v33, v32, v32
	v_fmac_f32_e32 v35, v34, v34
	v_add_f32_e32 v33, v33, v35
	v_add_f32_e32 v17, v17, v33
	v_cvt_pk_bf16_f32 v92, v36, v37
	v_cvt_pk_bf16_f32 v93, v38, v39
	global_store_dwordx2 v15, v[92:93], s[12:13] offset:0 sc0 sc1
	v_lshlrev_b32_e32 v36, 16, v92
	v_and_b32_e32 v37, 0xffff0000, v92
	v_lshlrev_b32_e32 v38, 16, v93
	v_and_b32_e32 v39, 0xffff0000, v93
	v_mul_f32_e32 v37, v37, v37
	v_mul_f32_e32 v39, v39, v39
	v_fmac_f32_e32 v37, v36, v36
	v_fmac_f32_e32 v39, v38, v38
	v_add_f32_e32 v37, v37, v39
	v_add_f32_e32 v17, v17, v37
	v_cvt_pk_bf16_f32 v94, v40, v41
	v_cvt_pk_bf16_f32 v95, v42, v43
	global_store_dwordx2 v15, v[94:95], s[12:13] offset:512 sc0 sc1
	v_lshlrev_b32_e32 v40, 16, v94
	v_and_b32_e32 v41, 0xffff0000, v94
	v_lshlrev_b32_e32 v42, 16, v95
	v_and_b32_e32 v43, 0xffff0000, v95
	v_mul_f32_e32 v41, v41, v41
	v_mul_f32_e32 v43, v43, v43
	v_fmac_f32_e32 v41, v40, v40
	v_fmac_f32_e32 v43, v42, v42
	v_add_f32_e32 v41, v41, v43
	v_add_f32_e32 v17, v17, v41
	v_cvt_pk_bf16_f32 v96, v44, v45
	v_cvt_pk_bf16_f32 v97, v46, v47
	global_store_dwordx2 v15, v[96:97], s[12:13] offset:1024 sc0 sc1
	v_lshlrev_b32_e32 v44, 16, v96
	v_and_b32_e32 v45, 0xffff0000, v96
	v_lshlrev_b32_e32 v46, 16, v97
	v_and_b32_e32 v47, 0xffff0000, v97
	v_mul_f32_e32 v45, v45, v45
	v_mul_f32_e32 v47, v47, v47
	v_fmac_f32_e32 v45, v44, v44
	v_fmac_f32_e32 v47, v46, v46
	v_add_f32_e32 v45, v45, v47
	v_add_f32_e32 v17, v17, v45
	v_cvt_pk_bf16_f32 v98, v48, v49
	v_cvt_pk_bf16_f32 v99, v50, v51
	global_store_dwordx2 v15, v[98:99], s[12:13] offset:1536 sc0 sc1
	v_lshlrev_b32_e32 v48, 16, v98
	v_and_b32_e32 v49, 0xffff0000, v98
	v_lshlrev_b32_e32 v50, 16, v99
	v_and_b32_e32 v51, 0xffff0000, v99
	v_mul_f32_e32 v49, v49, v49
	v_mul_f32_e32 v51, v51, v51
	v_fmac_f32_e32 v49, v48, v48
	v_fmac_f32_e32 v51, v50, v50
	v_add_f32_e32 v49, v49, v51
	v_add_f32_e32 v17, v17, v49
	ds_bpermute_b32 v18, v120, v17
	s_waitcnt lgkmcnt(0)
	v_add_f32_e32 v17, v17, v18
	ds_bpermute_b32 v18, v121, v17
	s_waitcnt lgkmcnt(0)
	v_add_f32_e32 v17, v17, v18
	ds_bpermute_b32 v18, v122, v17
	s_waitcnt lgkmcnt(0)
	v_add_f32_e32 v17, v17, v18
	ds_bpermute_b32 v18, v123, v17
	s_waitcnt lgkmcnt(0)
	v_add_f32_e32 v17, v17, v18
	ds_bpermute_b32 v18, v124, v17
	s_waitcnt lgkmcnt(0)
	v_add_f32_e32 v17, v17, v18
	ds_bpermute_b32 v18, v125, v17
	s_waitcnt lgkmcnt(0)
; __device__ __forceinline__ unsigned pk2(float lo, float hi) { return pg8::cvt_pk_bf16(lo, hi); }
; __device__ __forceinline__ void xcvt_pass(const Ctx& C, const float* X, bf16* XB) {
;     ...
;     for (int m = gw; m < M; m += NGW) {
;         const f32x4* xr = (const f32x4*)(X + (size_t)m * D) + C.lane; v2u* o = (v2u*)(XB + (size_t)m * D) + C.lane; float s = 0.f;
; #pragma unroll
;         for (int j = 0; j < 8; ++j) { const f32x4 v = __builtin_nontemporal_load(xr + 64 * j); const v2u w = (v2u){pk2(v[0], v[1]), pk2(v[2], v[3])}; o[64 * j] = w;
;             const float x0 = __uint_as_float(w.x << 16), x1 = __uint_as_float(w.x & 0xffff0000u), x2 = __uint_as_float(w.y << 16), x3 = __uint_as_float(w.y & 0xffff0000u);
;             s += (x0 * x0 + x1 * x1) + (x2 * x2 + x3 * x3); }
;         s = wave_sum(s);
;         if (C.lane < 32) SS[(size_t)m * 32 + C.lane] = C.lane == 0 ? s : 0.f;
;     }
	v_add_f32_e32 v17, v17, v18
	v_cmp_eq_u32_e32 vcc, 0, v1
	s_nop 1
	v_cndmask_b32_e32 v19, 0, v17, vcc
	s_mov_b64 s[8:9], exec
	s_mov_b32 exec_lo, -1
	s_mov_b32 exec_hi, 0
	global_store_dword v16, v19, s[14:15]
	s_mov_b64 exec, s[8:9]
	s_lshl_b32 s6, s58, 12
	s_add_u32 s12, s48, s6
	s_addc_u32 s13, s49, 0
	s_add_u32 s12, s12, 0x26100800
	s_addc_u32 s13, s13, 0
	s_lshl_b32 s6, s58, 7
	s_add_u32 s14, s48, s6
	s_addc_u32 s15, s49, 0
	s_add_u32 s14, s14, 0x25e00000
	s_addc_u32 s15, s15, 0
	s_add_u32 s58, s58, s44
	s_lshl_b32 s6, s58, 13
	s_lshr_b32 s7, s58, 19
	s_add_u32 s10, s64, s6
	s_addc_u32 s11, s65, s7
	s_add_u32 s10, s10, 0x1000
	s_addc_u32 s11, s11, 0
	global_load_dwordx4 v[20:23], v14, s[10:11] offset:-4096 nt
	global_load_dwordx4 v[24:27], v14, s[10:11] offset:-3072 nt
	global_load_dwordx4 v[28:31], v14, s[10:11] offset:-2048 nt
	global_load_dwordx4 v[32:35], v14, s[10:11] offset:-1024 nt
	global_load_dwordx4 v[36:39], v14, s[10:11] offset:0 nt
	global_load_dwordx4 v[40:43], v14, s[10:11] offset:1024 nt
	global_load_dwordx4 v[44:47], v14, s[10:11] offset:2048 nt
	global_load_dwordx4 v[48:51], v14, s[10:11] offset:3072 nt
	s_waitcnt vmcnt(17)
	v_cvt_pk_bf16_f32 v100, v52, v53
	v_cvt_pk_bf16_f32 v101, v54, v55
	global_store_dwordx2 v15, v[100:101], s[12:13] offset:-2048 sc0 sc1
	v_lshlrev_b32_e32 v52, 16, v100
	v_and_b32_e32 v53, 0xffff0000, v100
	v_lshlrev_b32_e32 v54, 16, v101
	v_and_b32_e32 v55, 0xffff0000, v101
	v_mul_f32_e32 v53, v53, v53
	v_mul_f32_e32 v55, v55, v55
	v_fmac_f32_e32 v53, v52, v52
	v_fmac_f32_e32 v55, v54, v54
	v_add_f32_e32 v17, v53, v55
	v_cvt_pk_bf16_f32 v102, v56, v57
	v_cvt_pk_bf16_f32 v103, v58, v59
	global_store_dwordx2 v15, v[102:103], s[12:13] offset:-1536 sc0 sc1
	v_lshlrev_b32_e32 v56, 16, v102
	v_and_b32_e32 v57, 0xffff0000, v102
	v_lshlrev_b32_e32 v58, 16, v103
	v_and_b32_e32 v59, 0xffff0000, v103
	v_mul_f32_e32 v57, v57, v57
	v_mul_f32_e32 v59, v59, v59
	v_fmac_f32_e32 v57, v56, v56
	v_fmac_f32_e32 v59, v58, v58
	v_add_f32_e32 v57, v57, v59
	v_add_f32_e32 v17, v17, v57
	v_cvt_pk_bf16_f32 v104, v60, v61
	v_cvt_pk_bf16_f32 v105, v62, v63
	global_store_dwordx2 v15, v[104:105], s[12:13] offset:-1024 sc0 sc1
	v_lshlrev_b32_e32 v60, 16, v104
	v_and_b32_e32 v61, 0xffff0000, v104
	v_lshlrev_b32_e32 v62, 16, v105
	v_and_b32_e32 v63, 0xffff0000, v105
	v_mul_f32_e32 v61, v61, v61
	v_mul_f32_e32 v63, v63, v63
	v_fmac_f32_e32 v61, v60, v60
	v_fmac_f32_e32 v63, v62, v62
	v_add_f32_e32 v61, v61, v63
	v_add_f32_e32 v17, v17, v61
	v_cvt_pk_bf16_f32 v106, v64, v65
	v_cvt_pk_bf16_f32 v107, v66, v67
	global_store_dwordx2 v15, v[106:107], s[12:13] offset:-512 sc0 sc1
	v_lshlrev_b32_e32 v64, 16, v106
	v_and_b32_e32 v65, 0xffff0000, v106
	v_lshlrev_b32_e32 v66, 16, v107
	v_and_b32_e32 v67, 0xffff0000, v107
	v_mul_f32_e32 v65, v65, v65
	v_mul_f32_e32 v67, v67, v67
	v_fmac_f32_e32 v65, v64, v64
	v_fmac_f32_e32 v67, v66, v66
	v_add_f32_e32 v65, v65, v67
	v_add_f32_e32 v17, v17, v65
	v_cvt_pk_bf16_f32 v108, v68, v69
	v_cvt_pk_bf16_f32 v109, v70, v71
	global_store_dwordx2 v15, v[108:109], s[12:13] offset:0 sc0 sc1
	v_lshlrev_b32_e32 v68, 16, v108
	v_and_b32_e32 v69, 0xffff0000, v108
	v_lshlrev_b32_e32 v70, 16, v109
	v_and_b32_e32 v71, 0xffff0000, v109
	v_mul_f32_e32 v69, v69, v69
	v_mul_f32_e32 v71, v71, v71
	v_fmac_f32_e32 v69, v68, v68
	v_fmac_f32_e32 v71, v70, v70
	v_add_f32_e32 v69, v69, v71
	v_add_f32_e32 v17, v17, v69
	v_cvt_pk_bf16_f32 v110, v72, v73
	v_cvt_pk_bf16_f32 v111, v74, v75
	global_store_dwordx2 v15, v[110:111], s[12:13] offset:512 sc0 sc1
	v_lshlrev_b32_e32 v72, 16, v110
	v_and_b32_e32 v73, 0xffff0000, v110
	v_lshlrev_b32_e32 v74, 16, v111
	v_and_b32_e32 v75, 0xffff0000, v111
	v_mul_f32_e32 v73, v73, v73
	v_mul_f32_e32 v75, v75, v75
	v_fmac_f32_e32 v73, v72, v72
	v_fmac_f32_e32 v75, v74, v74
	v_add_f32_e32 v73, v73, v75
	v_add_f32_e32 v17, v17, v73
	v_cvt_pk_bf16_f32 v112, v76, v77
	v_cvt_pk_bf16_f32 v113, v78, v79
	global_store_dwordx2 v15, v[112:113], s[12:13] offset:1024 sc0 sc1
	v_lshlrev_b32_e32 v76, 16, v112
	v_and_b32_e32 v77, 0xffff0000, v112
	v_lshlrev_b32_e32 v78, 16, v113
	v_and_b32_e32 v79, 0xffff0000, v113
	v_mul_f32_e32 v77, v77, v77
	v_mul_f32_e32 v79, v79, v79
	v_fmac_f32_e32 v77, v76, v76
	v_fmac_f32_e32 v79, v78, v78
	v_add_f32_e32 v77, v77, v79
	v_add_f32_e32 v17, v17, v77
	v_cvt_pk_bf16_f32 v114, v80, v81
	v_cvt_pk_bf16_f32 v115, v82, v83
	global_store_dwordx2 v15, v[114:115], s[12:13] offset:1536 sc0 sc1
	v_lshlrev_b32_e32 v80, 16, v114
	v_and_b32_e32 v81, 0xffff0000, v114
	v_lshlrev_b32_e32 v82, 16, v115
	v_and_b32_e32 v83, 0xffff0000, v115
	v_mul_f32_e32 v81, v81, v81
	v_mul_f32_e32 v83, v83, v83
	v_fmac_f32_e32 v81, v80, v80
	v_fmac_f32_e32 v83, v82, v82
	v_add_f32_e32 v81, v81, v83
	v_add_f32_e32 v17, v17, v81
	ds_bpermute_b32 v18, v120, v17
	s_waitcnt lgkmcnt(0)
	v_add_f32_e32 v17, v17, v18
	ds_bpermute_b32 v18, v121, v17
	s_waitcnt lgkmcnt(0)
	v_add_f32_e32 v17, v17, v18
	ds_bpermute_b32 v18, v122, v17
	s_waitcnt lgkmcnt(0)
	v_add_f32_e32 v17, v17, v18
	ds_bpermute_b32 v18, v123, v17
	s_waitcnt lgkmcnt(0)
	v_add_f32_e32 v17, v17, v18
	ds_bpermute_b32 v18, v124, v17
	s_waitcnt lgkmcnt(0)
	v_add_f32_e32 v17, v17, v18
	ds_bpermute_b32 v18, v125, v17
	s_waitcnt lgkmcnt(0)
; __device__ __forceinline__ unsigned pk2(float lo, float hi) { return pg8::cvt_pk_bf16(lo, hi); }
; __device__ __forceinline__ void xcvt_pass(const Ctx& C, const float* X, bf16* XB) {
;     ...
;     for (int m = gw; m < M; m += NGW) {
;         const f32x4* xr = (const f32x4*)(X + (size_t)m * D) + C.lane; v2u* o = (v2u*)(XB + (size_t)m * D) + C.lane; float s = 0.f;
; #pragma unroll
;         for (int j = 0; j < 8; ++j) { const f32x4 v = __builtin_nontemporal_load(xr + 64 * j); const v2u w = (v2u){pk2(v[0], v[1]), pk2(v[2], v[3])}; o[64 * j] = w;
;             const float x0 = __uint_as_float(w.x << 16), x1 = __uint_as_float(w.x & 0xffff0000u), x2 = __uint_as_float(w.y << 16), x3 = __uint_as_float(w.y & 0xffff0000u);
;             s += (x0 * x0 + x1 * x1) + (x2 * x2 + x3 * x3); }
;         s = wave_sum(s);
;         if (C.lane < 32) SS[(size_t)m * 32 + C.lane] = C.lane == 0 ? s : 0.f;
;     }
	v_add_f32_e32 v17, v17, v18
	v_cmp_eq_u32_e32 vcc, 0, v1
	s_nop 1
	v_cndmask_b32_e32 v19, 0, v17, vcc
	s_mov_b64 s[8:9], exec
	s_mov_b32 exec_lo, -1
	s_mov_b32 exec_hi, 0
	global_store_dword v16, v19, s[14:15]
	s_mov_b64 exec, s[8:9]
	s_lshl_b32 s6, s58, 12
	s_add_u32 s12, s48, s6
	s_addc_u32 s13, s49, 0
	s_add_u32 s12, s12, 0x26100800
	s_addc_u32 s13, s13, 0
	s_lshl_b32 s6, s58, 7
	s_add_u32 s14, s48, s6
	s_addc_u32 s15, s49, 0
	s_add_u32 s14, s14, 0x25e00000
	s_addc_u32 s15, s15, 0
	s_add_u32 s58, s58, s44
	s_lshl_b32 s6, s58, 13
	s_lshr_b32 s7, s58, 19
	s_add_u32 s10, s64, s6
	s_addc_u32 s11, s65, s7
	s_add_u32 s10, s10, 0x1000
	s_addc_u32 s11, s11, 0
	global_load_dwordx4 v[52:55], v14, s[10:11] offset:-4096 nt
	global_load_dwordx4 v[56:59], v14, s[10:11] offset:-3072 nt
	global_load_dwordx4 v[60:63], v14, s[10:11] offset:-2048 nt
	global_load_dwordx4 v[64:67], v14, s[10:11] offset:-1024 nt
	global_load_dwordx4 v[68:71], v14, s[10:11] offset:0 nt
	global_load_dwordx4 v[72:75], v14, s[10:11] offset:1024 nt
	global_load_dwordx4 v[76:79], v14, s[10:11] offset:2048 nt
	global_load_dwordx4 v[80:83], v14, s[10:11] offset:3072 nt
	s_waitcnt vmcnt(17)
	v_cvt_pk_bf16_f32 v84, v20, v21
	v_cvt_pk_bf16_f32 v85, v22, v23
	global_store_dwordx2 v15, v[84:85], s[12:13] offset:-2048 sc0 sc1
	v_lshlrev_b32_e32 v20, 16, v84
	v_and_b32_e32 v21, 0xffff0000, v84
	v_lshlrev_b32_e32 v22, 16, v85
	v_and_b32_e32 v23, 0xffff0000, v85
	v_mul_f32_e32 v21, v21, v21
	v_mul_f32_e32 v23, v23, v23
	v_fmac_f32_e32 v21, v20, v20
	v_fmac_f32_e32 v23, v22, v22
	v_add_f32_e32 v17, v21, v23
	v_cvt_pk_bf16_f32 v86, v24, v25
	v_cvt_pk_bf16_f32 v87, v26, v27
	global_store_dwordx2 v15, v[86:87], s[12:13] offset:-1536 sc0 sc1
	v_lshlrev_b32_e32 v24, 16, v86
	v_and_b32_e32 v25, 0xffff0000, v86
	v_lshlrev_b32_e32 v26, 16, v87
	v_and_b32_e32 v27, 0xffff0000, v87
	v_mul_f32_e32 v25, v25, v25
	v_mul_f32_e32 v27, v27, v27
	v_fmac_f32_e32 v25, v24, v24
	v_fmac_f32_e32 v27, v26, v26
	v_add_f32_e32 v25, v25, v27
	v_add_f32_e32 v17, v17, v25
	v_cvt_pk_bf16_f32 v88, v28, v29
	v_cvt_pk_bf16_f32 v89, v30, v31
	global_store_dwordx2 v15, v[88:89], s[12:13] offset:-1024 sc0 sc1
	v_lshlrev_b32_e32 v28, 16, v88
	v_and_b32_e32 v29, 0xffff0000, v88
	v_lshlrev_b32_e32 v30, 16, v89
	v_and_b32_e32 v31, 0xffff0000, v89
	v_mul_f32_e32 v29, v29, v29
	v_mul_f32_e32 v31, v31, v31
	v_fmac_f32_e32 v29, v28, v28
	v_fmac_f32_e32 v31, v30, v30
	v_add_f32_e32 v29, v29, v31
	v_add_f32_e32 v17, v17, v29
	v_cvt_pk_bf16_f32 v90, v32, v33
	v_cvt_pk_bf16_f32 v91, v34, v35
	global_store_dwordx2 v15, v[90:91], s[12:13] offset:-512 sc0 sc1
	v_lshlrev_b32_e32 v32, 16, v90
	v_and_b32_e32 v33, 0xffff0000, v90
	v_lshlrev_b32_e32 v34, 16, v91
	v_and_b32_e32 v35, 0xffff0000, v91
	v_mul_f32_e32 v33, v33, v33
	v_mul_f32_e32 v35, v35, v35
	v_fmac_f32_e32 v33, v32, v32
	v_fmac_f32_e32 v35, v34, v34
	v_add_f32_e32 v33, v33, v35
	v_add_f32_e32 v17, v17, v33
	v_cvt_pk_bf16_f32 v92, v36, v37
	v_cvt_pk_bf16_f32 v93, v38, v39
	global_store_dwordx2 v15, v[92:93], s[12:13] offset:0 sc0 sc1
	v_lshlrev_b32_e32 v36, 16, v92
	v_and_b32_e32 v37, 0xffff0000, v92
	v_lshlrev_b32_e32 v38, 16, v93
	v_and_b32_e32 v39, 0xffff0000, v93
	v_mul_f32_e32 v37, v37, v37
	v_mul_f32_e32 v39, v39, v39
	v_fmac_f32_e32 v37, v36, v36
	v_fmac_f32_e32 v39, v38, v38
	v_add_f32_e32 v37, v37, v39
	v_add_f32_e32 v17, v17, v37
	v_cvt_pk_bf16_f32 v94, v40, v41
	v_cvt_pk_bf16_f32 v95, v42, v43
	global_store_dwordx2 v15, v[94:95], s[12:13] offset:512 sc0 sc1
	v_lshlrev_b32_e32 v40, 16, v94
	v_and_b32_e32 v41, 0xffff0000, v94
	v_lshlrev_b32_e32 v42, 16, v95
	v_and_b32_e32 v43, 0xffff0000, v95
	v_mul_f32_e32 v41, v41, v41
	v_mul_f32_e32 v43, v43, v43
	v_fmac_f32_e32 v41, v40, v40
	v_fmac_f32_e32 v43, v42, v42
	v_add_f32_e32 v41, v41, v43
	v_add_f32_e32 v17, v17, v41
	v_cvt_pk_bf16_f32 v96, v44, v45
	v_cvt_pk_bf16_f32 v97, v46, v47
	global_store_dwordx2 v15, v[96:97], s[12:13] offset:1024 sc0 sc1
	v_lshlrev_b32_e32 v44, 16, v96
	v_and_b32_e32 v45, 0xffff0000, v96
	v_lshlrev_b32_e32 v46, 16, v97
	v_and_b32_e32 v47, 0xffff0000, v97
	v_mul_f32_e32 v45, v45, v45
	v_mul_f32_e32 v47, v47, v47
	v_fmac_f32_e32 v45, v44, v44
	v_fmac_f32_e32 v47, v46, v46
	v_add_f32_e32 v45, v45, v47
	v_add_f32_e32 v17, v17, v45
	v_cvt_pk_bf16_f32 v98, v48, v49
	v_cvt_pk_bf16_f32 v99, v50, v51
	global_store_dwordx2 v15, v[98:99], s[12:13] offset:1536 sc0 sc1
	v_lshlrev_b32_e32 v48, 16, v98
	v_and_b32_e32 v49, 0xffff0000, v98
	v_lshlrev_b32_e32 v50, 16, v99
	v_and_b32_e32 v51, 0xffff0000, v99
	v_mul_f32_e32 v49, v49, v49
	v_mul_f32_e32 v51, v51, v51
	v_fmac_f32_e32 v49, v48, v48
	v_fmac_f32_e32 v51, v50, v50
	v_add_f32_e32 v49, v49, v51
	v_add_f32_e32 v17, v17, v49
	ds_bpermute_b32 v18, v120, v17
	s_waitcnt lgkmcnt(0)
	v_add_f32_e32 v17, v17, v18
	ds_bpermute_b32 v18, v121, v17
	s_waitcnt lgkmcnt(0)
	v_add_f32_e32 v17, v17, v18
	ds_bpermute_b32 v18, v122, v17
	s_waitcnt lgkmcnt(0)
	v_add_f32_e32 v17, v17, v18
	ds_bpermute_b32 v18, v123, v17
	s_waitcnt lgkmcnt(0)
	v_add_f32_e32 v17, v17, v18
	ds_bpermute_b32 v18, v124, v17
	s_waitcnt lgkmcnt(0)
	v_add_f32_e32 v17, v17, v18
	ds_bpermute_b32 v18, v125, v17
	s_waitcnt lgkmcnt(0)
; __device__ __forceinline__ unsigned pk2(float lo, float hi) { return pg8::cvt_pk_bf16(lo, hi); }
; __device__ __forceinline__ void xcvt_pass(const Ctx& C, const float* X, bf16* XB) {
;     ...
;     for (int m = gw; m < M; m += NGW) {
;         const f32x4* xr = (const f32x4*)(X + (size_t)m * D) + C.lane; v2u* o = (v2u*)(XB + (size_t)m * D) + C.lane; float s = 0.f;
; #pragma unroll
;         for (int j = 0; j < 8; ++j) { const f32x4 v = __builtin_nontemporal_load(xr + 64 * j); const v2u w = (v2u){pk2(v[0], v[1]), pk2(v[2], v[3])}; o[64 * j] = w;
;             const float x0 = __uint_as_float(w.x << 16), x1 = __uint_as_float(w.x & 0xffff0000u), x2 = __uint_as_float(w.y << 16), x3 = __uint_as_float(w.y & 0xffff0000u);
;             s += (x0 * x0 + x1 * x1) + (x2 * x2 + x3 * x3); }
;         s = wave_sum(s);
;         if (C.lane < 32) SS[(size_t)m * 32 + C.lane] = C.lane == 0 ? s : 0.f;
;     }
	v_add_f32_e32 v17, v17, v18
	v_cmp_eq_u32_e32 vcc, 0, v1
	s_nop 1
	v_cndmask_b32_e32 v19, 0, v17, vcc
	s_mov_b64 s[8:9], exec
	s_mov_b32 exec_lo, -1
	s_mov_b32 exec_hi, 0
	global_store_dword v16, v19, s[14:15]
	s_mov_b64 exec, s[8:9]
	s_lshl_b32 s6, s58, 12
	s_add_u32 s12, s48, s6
	s_addc_u32 s13, s49, 0
	s_add_u32 s12, s12, 0x26100800
	s_addc_u32 s13, s13, 0
	s_lshl_b32 s6, s58, 7
	s_add_u32 s14, s48, s6
	s_addc_u32 s15, s49, 0
	s_add_u32 s14, s14, 0x25e00000
	s_addc_u32 s15, s15, 0
	s_add_u32 s58, s58, s44
	s_lshl_b32 s6, s58, 13
	s_lshr_b32 s7, s58, 19
	s_add_u32 s10, s64, s6
	s_addc_u32 s11, s65, s7
	s_add_u32 s10, s10, 0x1000
	s_addc_u32 s11, s11, 0
	global_load_dwordx4 v[20:23], v14, s[10:11] offset:-4096 nt
	global_load_dwordx4 v[24:27], v14, s[10:11] offset:-3072 nt
	global_load_dwordx4 v[28:31], v14, s[10:11] offset:-2048 nt
	global_load_dwordx4 v[32:35], v14, s[10:11] offset:-1024 nt
	global_load_dwordx4 v[36:39], v14, s[10:11] offset:0 nt
	global_load_dwordx4 v[40:43], v14, s[10:11] offset:1024 nt
	global_load_dwordx4 v[44:47], v14, s[10:11] offset:2048 nt
	global_load_dwordx4 v[48:51], v14, s[10:11] offset:3072 nt
	s_waitcnt vmcnt(17)
	v_cvt_pk_bf16_f32 v100, v52, v53
	v_cvt_pk_bf16_f32 v101, v54, v55
	global_store_dwordx2 v15, v[100:101], s[12:13] offset:-2048 sc0 sc1
	v_lshlrev_b32_e32 v52, 16, v100
	v_and_b32_e32 v53, 0xffff0000, v100
	v_lshlrev_b32_e32 v54, 16, v101
	v_and_b32_e32 v55, 0xffff0000, v101
	v_mul_f32_e32 v53, v53, v53
	v_mul_f32_e32 v55, v55, v55
	v_fmac_f32_e32 v53, v52, v52
	v_fmac_f32_e32 v55, v54, v54
	v_add_f32_e32 v17, v53, v55
	v_cvt_pk_bf16_f32 v102, v56, v57
	v_cvt_pk_bf16_f32 v103, v58, v59
	global_store_dwordx2 v15, v[102:103], s[12:13] offset:-1536 sc0 sc1
	v_lshlrev_b32_e32 v56, 16, v102
	v_and_b32_e32 v57, 0xffff0000, v102
	v_lshlrev_b32_e32 v58, 16, v103
	v_and_b32_e32 v59, 0xffff0000, v103
	v_mul_f32_e32 v57, v57, v57
	v_mul_f32_e32 v59, v59, v59
	v_fmac_f32_e32 v57, v56, v56
	v_fmac_f32_e32 v59, v58, v58
	v_add_f32_e32 v57, v57, v59
	v_add_f32_e32 v17, v17, v57
	v_cvt_pk_bf16_f32 v104, v60, v61
	v_cvt_pk_bf16_f32 v105, v62, v63
	global_store_dwordx2 v15, v[104:105], s[12:13] offset:-1024 sc0 sc1
	v_lshlrev_b32_e32 v60, 16, v104
	v_and_b32_e32 v61, 0xffff0000, v104
	v_lshlrev_b32_e32 v62, 16, v105
	v_and_b32_e32 v63, 0xffff0000, v105
	v_mul_f32_e32 v61, v61, v61
	v_mul_f32_e32 v63, v63, v63
	v_fmac_f32_e32 v61, v60, v60
	v_fmac_f32_e32 v63, v62, v62
	v_add_f32_e32 v61, v61, v63
	v_add_f32_e32 v17, v17, v61
	v_cvt_pk_bf16_f32 v106, v64, v65
	v_cvt_pk_bf16_f32 v107, v66, v67
	global_store_dwordx2 v15, v[106:107], s[12:13] offset:-512 sc0 sc1
	v_lshlrev_b32_e32 v64, 16, v106
	v_and_b32_e32 v65, 0xffff0000, v106
	v_lshlrev_b32_e32 v66, 16, v107
	v_and_b32_e32 v67, 0xffff0000, v107
	v_mul_f32_e32 v65, v65, v65
	v_mul_f32_e32 v67, v67, v67
	v_fmac_f32_e32 v65, v64, v64
	v_fmac_f32_e32 v67, v66, v66
	v_add_f32_e32 v65, v65, v67
	v_add_f32_e32 v17, v17, v65
	v_cvt_pk_bf16_f32 v108, v68, v69
	v_cvt_pk_bf16_f32 v109, v70, v71
	global_store_dwordx2 v15, v[108:109], s[12:13] offset:0 sc0 sc1
	v_lshlrev_b32_e32 v68, 16, v108
	v_and_b32_e32 v69, 0xffff0000, v108
	v_lshlrev_b32_e32 v70, 16, v109
	v_and_b32_e32 v71, 0xffff0000, v109
	v_mul_f32_e32 v69, v69, v69
	v_mul_f32_e32 v71, v71, v71
	v_fmac_f32_e32 v69, v68, v68
	v_fmac_f32_e32 v71, v70, v70
	v_add_f32_e32 v69, v69, v71
	v_add_f32_e32 v17, v17, v69
	v_cvt_pk_bf16_f32 v110, v72, v73
	v_cvt_pk_bf16_f32 v111, v74, v75
	global_store_dwordx2 v15, v[110:111], s[12:13] offset:512 sc0 sc1
	v_lshlrev_b32_e32 v72, 16, v110
	v_and_b32_e32 v73, 0xffff0000, v110
	v_lshlrev_b32_e32 v74, 16, v111
	v_and_b32_e32 v75, 0xffff0000, v111
	v_mul_f32_e32 v73, v73, v73
	v_mul_f32_e32 v75, v75, v75
	v_fmac_f32_e32 v73, v72, v72
	v_fmac_f32_e32 v75, v74, v74
	v_add_f32_e32 v73, v73, v75
	v_add_f32_e32 v17, v17, v73
	v_cvt_pk_bf16_f32 v112, v76, v77
	v_cvt_pk_bf16_f32 v113, v78, v79
	global_store_dwordx2 v15, v[112:113], s[12:13] offset:1024 sc0 sc1
	v_lshlrev_b32_e32 v76, 16, v112
	v_and_b32_e32 v77, 0xffff0000, v112
	v_lshlrev_b32_e32 v78, 16, v113
	v_and_b32_e32 v79, 0xffff0000, v113
	v_mul_f32_e32 v77, v77, v77
	v_mul_f32_e32 v79, v79, v79
	v_fmac_f32_e32 v77, v76, v76
	v_fmac_f32_e32 v79, v78, v78
	v_add_f32_e32 v77, v77, v79
	v_add_f32_e32 v17, v17, v77
	v_cvt_pk_bf16_f32 v114, v80, v81
	v_cvt_pk_bf16_f32 v115, v82, v83
	global_store_dwordx2 v15, v[114:115], s[12:13] offset:1536 sc0 sc1
	v_lshlrev_b32_e32 v80, 16, v114
	v_and_b32_e32 v81, 0xffff0000, v114
	v_lshlrev_b32_e32 v82, 16, v115
	v_and_b32_e32 v83, 0xffff0000, v115
	v_mul_f32_e32 v81, v81, v81
	v_mul_f32_e32 v83, v83, v83
	v_fmac_f32_e32 v81, v80, v80
	v_fmac_f32_e32 v83, v82, v82
	v_add_f32_e32 v81, v81, v83
	v_add_f32_e32 v17, v17, v81
	ds_bpermute_b32 v18, v120, v17
	s_waitcnt lgkmcnt(0)
	v_add_f32_e32 v17, v17, v18
	ds_bpermute_b32 v18, v121, v17
	s_waitcnt lgkmcnt(0)
	v_add_f32_e32 v17, v17, v18
	ds_bpermute_b32 v18, v122, v17
	s_waitcnt lgkmcnt(0)
	v_add_f32_e32 v17, v17, v18
	ds_bpermute_b32 v18, v123, v17
	s_waitcnt lgkmcnt(0)
	v_add_f32_e32 v17, v17, v18
	ds_bpermute_b32 v18, v124, v17
	s_waitcnt lgkmcnt(0)
	v_add_f32_e32 v17, v17, v18
	ds_bpermute_b32 v18, v125, v17
	s_waitcnt lgkmcnt(0)
; __device__ __forceinline__ unsigned pk2(float lo, float hi) { return pg8::cvt_pk_bf16(lo, hi); }
; __device__ __forceinline__ void xcvt_pass(const Ctx& C, const float* X, bf16* XB) {
;     ...
;     for (int m = gw; m < M; m += NGW) {
;         const f32x4* xr = (const f32x4*)(X + (size_t)m * D) + C.lane; v2u* o = (v2u*)(XB + (size_t)m * D) + C.lane; float s = 0.f;
; #pragma unroll
;         for (int j = 0; j < 8; ++j) { const f32x4 v = __builtin_nontemporal_load(xr + 64 * j); const v2u w = (v2u){pk2(v[0], v[1]), pk2(v[2], v[3])}; o[64 * j] = w;
;             const float x0 = __uint_as_float(w.x << 16), x1 = __uint_as_float(w.x & 0xffff0000u), x2 = __uint_as_float(w.y << 16), x3 = __uint_as_float(w.y & 0xffff0000u);
;             s += (x0 * x0 + x1 * x1) + (x2 * x2 + x3 * x3); }
;         s = wave_sum(s);
;         if (C.lane < 32) SS[(size_t)m * 32 + C.lane] = C.lane == 0 ? s : 0.f;
;     }
	v_add_f32_e32 v17, v17, v18
	v_cmp_eq_u32_e32 vcc, 0, v1
	s_nop 1
	v_cndmask_b32_e32 v19, 0, v17, vcc
	s_mov_b64 s[8:9], exec
	s_mov_b32 exec_lo, -1
	s_mov_b32 exec_hi, 0
	global_store_dword v16, v19, s[14:15]
	s_mov_b64 exec, s[8:9]
	s_lshl_b32 s6, s58, 12
	s_add_u32 s12, s48, s6
	s_addc_u32 s13, s49, 0
	s_add_u32 s12, s12, 0x26100800
	s_addc_u32 s13, s13, 0
	s_lshl_b32 s6, s58, 7
	s_add_u32 s14, s48, s6
	s_addc_u32 s15, s49, 0
	s_add_u32 s14, s14, 0x25e00000
	s_addc_u32 s15, s15, 0
	s_add_u32 s58, s58, s44
	s_lshl_b32 s6, s58, 13
	s_lshr_b32 s7, s58, 19
	s_add_u32 s10, s64, s6
	s_addc_u32 s11, s65, s7
	s_add_u32 s10, s10, 0x1000
	s_addc_u32 s11, s11, 0
	global_load_dwordx4 v[52:55], v14, s[10:11] offset:-4096 nt
	global_load_dwordx4 v[56:59], v14, s[10:11] offset:-3072 nt
	global_load_dwordx4 v[60:63], v14, s[10:11] offset:-2048 nt
	global_load_dwordx4 v[64:67], v14, s[10:11] offset:-1024 nt
	global_load_dwordx4 v[68:71], v14, s[10:11] offset:0 nt
	global_load_dwordx4 v[72:75], v14, s[10:11] offset:1024 nt
	global_load_dwordx4 v[76:79], v14, s[10:11] offset:2048 nt
	global_load_dwordx4 v[80:83], v14, s[10:11] offset:3072 nt
	s_waitcnt vmcnt(17)
	v_cvt_pk_bf16_f32 v84, v20, v21
	v_cvt_pk_bf16_f32 v85, v22, v23
	global_store_dwordx2 v15, v[84:85], s[12:13] offset:-2048 sc0 sc1
	v_lshlrev_b32_e32 v20, 16, v84
	v_and_b32_e32 v21, 0xffff0000, v84
	v_lshlrev_b32_e32 v22, 16, v85
	v_and_b32_e32 v23, 0xffff0000, v85
	v_mul_f32_e32 v21, v21, v21
	v_mul_f32_e32 v23, v23, v23
	v_fmac_f32_e32 v21, v20, v20
	v_fmac_f32_e32 v23, v22, v22
	v_add_f32_e32 v17, v21, v23
	v_cvt_pk_bf16_f32 v86, v24, v25
	v_cvt_pk_bf16_f32 v87, v26, v27
	global_store_dwordx2 v15, v[86:87], s[12:13] offset:-1536 sc0 sc1
	v_lshlrev_b32_e32 v24, 16, v86
	v_and_b32_e32 v25, 0xffff0000, v86
	v_lshlrev_b32_e32 v26, 16, v87
	v_and_b32_e32 v27, 0xffff0000, v87
	v_mul_f32_e32 v25, v25, v25
	v_mul_f32_e32 v27, v27, v27
	v_fmac_f32_e32 v25, v24, v24
	v_fmac_f32_e32 v27, v26, v26
	v_add_f32_e32 v25, v25, v27
	v_add_f32_e32 v17, v17, v25
	v_cvt_pk_bf16_f32 v88, v28, v29
	v_cvt_pk_bf16_f32 v89, v30, v31
	global_store_dwordx2 v15, v[88:89], s[12:13] offset:-1024 sc0 sc1
	v_lshlrev_b32_e32 v28, 16, v88
	v_and_b32_e32 v29, 0xffff0000, v88
	v_lshlrev_b32_e32 v30, 16, v89
	v_and_b32_e32 v31, 0xffff0000, v89
	v_mul_f32_e32 v29, v29, v29
	v_mul_f32_e32 v31, v31, v31
	v_fmac_f32_e32 v29, v28, v28
	v_fmac_f32_e32 v31, v30, v30
	v_add_f32_e32 v29, v29, v31
	v_add_f32_e32 v17, v17, v29
	v_cvt_pk_bf16_f32 v90, v32, v33
	v_cvt_pk_bf16_f32 v91, v34, v35
	global_store_dwordx2 v15, v[90:91], s[12:13] offset:-512 sc0 sc1
	v_lshlrev_b32_e32 v32, 16, v90
	v_and_b32_e32 v33, 0xffff0000, v90
	v_lshlrev_b32_e32 v34, 16, v91
	v_and_b32_e32 v35, 0xffff0000, v91
	v_mul_f32_e32 v33, v33, v33
	v_mul_f32_e32 v35, v35, v35
	v_fmac_f32_e32 v33, v32, v32
	v_fmac_f32_e32 v35, v34, v34
	v_add_f32_e32 v33, v33, v35
	v_add_f32_e32 v17, v17, v33
	v_cvt_pk_bf16_f32 v92, v36, v37
	v_cvt_pk_bf16_f32 v93, v38, v39
	global_store_dwordx2 v15, v[92:93], s[12:13] offset:0 sc0 sc1
	v_lshlrev_b32_e32 v36, 16, v92
	v_and_b32_e32 v37, 0xffff0000, v92
	v_lshlrev_b32_e32 v38, 16, v93
	v_and_b32_e32 v39, 0xffff0000, v93
	v_mul_f32_e32 v37, v37, v37
	v_mul_f32_e32 v39, v39, v39
	v_fmac_f32_e32 v37, v36, v36
	v_fmac_f32_e32 v39, v38, v38
	v_add_f32_e32 v37, v37, v39
	v_add_f32_e32 v17, v17, v37
	v_cvt_pk_bf16_f32 v94, v40, v41
	v_cvt_pk_bf16_f32 v95, v42, v43
	global_store_dwordx2 v15, v[94:95], s[12:13] offset:512 sc0 sc1
	v_lshlrev_b32_e32 v40, 16, v94
	v_and_b32_e32 v41, 0xffff0000, v94
	v_lshlrev_b32_e32 v42, 16, v95
	v_and_b32_e32 v43, 0xffff0000, v95
	v_mul_f32_e32 v41, v41, v41
	v_mul_f32_e32 v43, v43, v43
	v_fmac_f32_e32 v41, v40, v40
	v_fmac_f32_e32 v43, v42, v42
	v_add_f32_e32 v41, v41, v43
	v_add_f32_e32 v17, v17, v41
	v_cvt_pk_bf16_f32 v96, v44, v45
	v_cvt_pk_bf16_f32 v97, v46, v47
	global_store_dwordx2 v15, v[96:97], s[12:13] offset:1024 sc0 sc1
	v_lshlrev_b32_e32 v44, 16, v96
	v_and_b32_e32 v45, 0xffff0000, v96
	v_lshlrev_b32_e32 v46, 16, v97
	v_and_b32_e32 v47, 0xffff0000, v97
	v_mul_f32_e32 v45, v45, v45
	v_mul_f32_e32 v47, v47, v47
	v_fmac_f32_e32 v45, v44, v44
	v_fmac_f32_e32 v47, v46, v46
	v_add_f32_e32 v45, v45, v47
	v_add_f32_e32 v17, v17, v45
	v_cvt_pk_bf16_f32 v98, v48, v49
	v_cvt_pk_bf16_f32 v99, v50, v51
	global_store_dwordx2 v15, v[98:99], s[12:13] offset:1536 sc0 sc1
	v_lshlrev_b32_e32 v48, 16, v98
	v_and_b32_e32 v49, 0xffff0000, v98
	v_lshlrev_b32_e32 v50, 16, v99
	v_and_b32_e32 v51, 0xffff0000, v99
	v_mul_f32_e32 v49, v49, v49
	v_mul_f32_e32 v51, v51, v51
	v_fmac_f32_e32 v49, v48, v48
	v_fmac_f32_e32 v51, v50, v50
	v_add_f32_e32 v49, v49, v51
	v_add_f32_e32 v17, v17, v49
	ds_bpermute_b32 v18, v120, v17
	s_waitcnt lgkmcnt(0)
	v_add_f32_e32 v17, v17, v18
	ds_bpermute_b32 v18, v121, v17
	s_waitcnt lgkmcnt(0)
	v_add_f32_e32 v17, v17, v18
	ds_bpermute_b32 v18, v122, v17
	s_waitcnt lgkmcnt(0)
	v_add_f32_e32 v17, v17, v18
	ds_bpermute_b32 v18, v123, v17
	s_waitcnt lgkmcnt(0)
; __device__ __forceinline__ unsigned pk2(float lo, float hi) { return pg8::cvt_pk_bf16(lo, hi); }
; __device__ __forceinline__ void xcvt_pass(const Ctx& C, const float* X, bf16* XB) {
;     ...
;     for (int m = gw; m < M; m += NGW) {
;         const f32x4* xr = (const f32x4*)(X + (size_t)m * D) + C.lane; v2u* o = (v2u*)(XB + (size_t)m * D) + C.lane; float s = 0.f;
; #pragma unroll
;         for (int j = 0; j < 8; ++j) { const f32x4 v = __builtin_nontemporal_load(xr + 64 * j); const v2u w = (v2u){pk2(v[0], v[1]), pk2(v[2], v[3])}; o[64 * j] = w;
;             const float x0 = __uint_as_float(w.x << 16), x1 = __uint_as_float(w.x & 0xffff0000u), x2 = __uint_as_float(w.y << 16), x3 = __uint_as_float(w.y & 0xffff0000u);
;             s += (x0 * x0 + x1 * x1) + (x2 * x2 + x3 * x3); }
;         s = wave_sum(s);
;         if (C.lane < 32) SS[(size_t)m * 32 + C.lane] = C.lane == 0 ? s : 0.f;
;     }
	v_add_f32_e32 v17, v17, v18
	ds_bpermute_b32 v18, v124, v17
	s_waitcnt lgkmcnt(0)
	v_add_f32_e32 v17, v17, v18
	ds_bpermute_b32 v18, v125, v17
	s_waitcnt lgkmcnt(0)
	v_add_f32_e32 v17, v17, v18
	v_cmp_eq_u32_e32 vcc, 0, v1
	s_nop 1
	v_cndmask_b32_e32 v19, 0, v17, vcc
	s_mov_b64 s[8:9], exec
	s_mov_b32 exec_lo, -1
	s_mov_b32 exec_hi, 0
	global_store_dword v16, v19, s[14:15]
	s_mov_b64 exec, s[8:9]
	s_lshl_b32 s6, s58, 12
	s_add_u32 s12, s48, s6
	s_addc_u32 s13, s49, 0
	s_add_u32 s12, s12, 0x26100800
	s_addc_u32 s13, s13, 0
	s_lshl_b32 s6, s58, 7
	s_add_u32 s14, s48, s6
	s_addc_u32 s15, s49, 0
	s_add_u32 s14, s14, 0x25e00000
	s_addc_u32 s15, s15, 0
	s_waitcnt vmcnt(9)
	v_cvt_pk_bf16_f32 v100, v52, v53
	v_cvt_pk_bf16_f32 v101, v54, v55
	global_store_dwordx2 v15, v[100:101], s[12:13] offset:-2048 sc0 sc1
	v_lshlrev_b32_e32 v52, 16, v100
	v_and_b32_e32 v53, 0xffff0000, v100
	v_lshlrev_b32_e32 v54, 16, v101
	v_and_b32_e32 v55, 0xffff0000, v101
	v_mul_f32_e32 v53, v53, v53
	v_mul_f32_e32 v55, v55, v55
	v_fmac_f32_e32 v53, v52, v52
	v_fmac_f32_e32 v55, v54, v54
	v_add_f32_e32 v17, v53, v55
	v_cvt_pk_bf16_f32 v102, v56, v57
	v_cvt_pk_bf16_f32 v103, v58, v59
	global_store_dwordx2 v15, v[102:103], s[12:13] offset:-1536 sc0 sc1
	v_lshlrev_b32_e32 v56, 16, v102
	v_and_b32_e32 v57, 0xffff0000, v102
	v_lshlrev_b32_e32 v58, 16, v103
	v_and_b32_e32 v59, 0xffff0000, v103
	v_mul_f32_e32 v57, v57, v57
	v_mul_f32_e32 v59, v59, v59
	v_fmac_f32_e32 v57, v56, v56
	v_fmac_f32_e32 v59, v58, v58
	v_add_f32_e32 v57, v57, v59
	v_add_f32_e32 v17, v17, v57
	v_cvt_pk_bf16_f32 v104, v60, v61
	v_cvt_pk_bf16_f32 v105, v62, v63
	global_store_dwordx2 v15, v[104:105], s[12:13] offset:-1024 sc0 sc1
	v_lshlrev_b32_e32 v60, 16, v104
	v_and_b32_e32 v61, 0xffff0000, v104
	v_lshlrev_b32_e32 v62, 16, v105
	v_and_b32_e32 v63, 0xffff0000, v105
	v_mul_f32_e32 v61, v61, v61
	v_mul_f32_e32 v63, v63, v63
	v_fmac_f32_e32 v61, v60, v60
	v_fmac_f32_e32 v63, v62, v62
	v_add_f32_e32 v61, v61, v63
	v_add_f32_e32 v17, v17, v61
	v_cvt_pk_bf16_f32 v106, v64, v65
	v_cvt_pk_bf16_f32 v107, v66, v67
	global_store_dwordx2 v15, v[106:107], s[12:13] offset:-512 sc0 sc1
	v_lshlrev_b32_e32 v64, 16, v106
	v_and_b32_e32 v65, 0xffff0000, v106
	v_lshlrev_b32_e32 v66, 16, v107
	v_and_b32_e32 v67, 0xffff0000, v107
	v_mul_f32_e32 v65, v65, v65
	v_mul_f32_e32 v67, v67, v67
	v_fmac_f32_e32 v65, v64, v64
	v_fmac_f32_e32 v67, v66, v66
	v_add_f32_e32 v65, v65, v67
	v_add_f32_e32 v17, v17, v65
	v_cvt_pk_bf16_f32 v108, v68, v69
	v_cvt_pk_bf16_f32 v109, v70, v71
	global_store_dwordx2 v15, v[108:109], s[12:13] offset:0 sc0 sc1
	v_lshlrev_b32_e32 v68, 16, v108
	v_and_b32_e32 v69, 0xffff0000, v108
	v_lshlrev_b32_e32 v70, 16, v109
	v_and_b32_e32 v71, 0xffff0000, v109
	v_mul_f32_e32 v69, v69, v69
	v_mul_f32_e32 v71, v71, v71
	v_fmac_f32_e32 v69, v68, v68
	v_fmac_f32_e32 v71, v70, v70
	v_add_f32_e32 v69, v69, v71
	v_add_f32_e32 v17, v17, v69
	v_cvt_pk_bf16_f32 v110, v72, v73
	v_cvt_pk_bf16_f32 v111, v74, v75
	global_store_dwordx2 v15, v[110:111], s[12:13] offset:512 sc0 sc1
	v_lshlrev_b32_e32 v72, 16, v110
	v_and_b32_e32 v73, 0xffff0000, v110
	v_lshlrev_b32_e32 v74, 16, v111
	v_and_b32_e32 v75, 0xffff0000, v111
	v_mul_f32_e32 v73, v73, v73
	v_mul_f32_e32 v75, v75, v75
	v_fmac_f32_e32 v73, v72, v72
	v_fmac_f32_e32 v75, v74, v74
	v_add_f32_e32 v73, v73, v75
	v_add_f32_e32 v17, v17, v73
	v_cvt_pk_bf16_f32 v112, v76, v77
	v_cvt_pk_bf16_f32 v113, v78, v79
	global_store_dwordx2 v15, v[112:113], s[12:13] offset:1024 sc0 sc1
	v_lshlrev_b32_e32 v76, 16, v112
	v_and_b32_e32 v77, 0xffff0000, v112
	v_lshlrev_b32_e32 v78, 16, v113
	v_and_b32_e32 v79, 0xffff0000, v113
	v_mul_f32_e32 v77, v77, v77
	v_mul_f32_e32 v79, v79, v79
	v_fmac_f32_e32 v77, v76, v76
	v_fmac_f32_e32 v79, v78, v78
	v_add_f32_e32 v77, v77, v79
	v_add_f32_e32 v17, v17, v77
	v_cvt_pk_bf16_f32 v114, v80, v81
	v_cvt_pk_bf16_f32 v115, v82, v83
	global_store_dwordx2 v15, v[114:115], s[12:13] offset:1536 sc0 sc1
	v_lshlrev_b32_e32 v80, 16, v114
	v_and_b32_e32 v81, 0xffff0000, v114
	v_lshlrev_b32_e32 v82, 16, v115
	v_and_b32_e32 v83, 0xffff0000, v115
	v_mul_f32_e32 v81, v81, v81
	v_mul_f32_e32 v83, v83, v83
	v_fmac_f32_e32 v81, v80, v80
	v_fmac_f32_e32 v83, v82, v82
	v_add_f32_e32 v81, v81, v83
	v_add_f32_e32 v17, v17, v81
	ds_bpermute_b32 v18, v120, v17
	s_waitcnt lgkmcnt(0)
	v_add_f32_e32 v17, v17, v18
	ds_bpermute_b32 v18, v121, v17
	s_waitcnt lgkmcnt(0)
	v_add_f32_e32 v17, v17, v18
	ds_bpermute_b32 v18, v122, v17
	s_waitcnt lgkmcnt(0)
	v_add_f32_e32 v17, v17, v18
	ds_bpermute_b32 v18, v123, v17
	s_waitcnt lgkmcnt(0)
	v_add_f32_e32 v17, v17, v18
	ds_bpermute_b32 v18, v124, v17
	s_waitcnt lgkmcnt(0)
	v_add_f32_e32 v17, v17, v18
	ds_bpermute_b32 v18, v125, v17
	s_waitcnt lgkmcnt(0)
	v_add_f32_e32 v17, v17, v18
	v_cmp_eq_u32_e32 vcc, 0, v1
	s_nop 1
	v_cndmask_b32_e32 v19, 0, v17, vcc
	s_mov_b64 s[8:9], exec
	s_mov_b32 exec_lo, -1
	s_mov_b32 exec_hi, 0
	global_store_dword v16, v19, s[14:15]
	s_mov_b64 exec, s[8:9]
	s_ashr_i32 s3, s2, 31
	v_mbcnt_lo_u32_b32 v235, -1, 0
